# rwkv scan: per-lane address constants of the staged rows packed once per unit; scalar chunk base
# speedup vs baseline: 1.0576x; 1.0138x over previous
; DI void rwkv_chunk_scan_phase(const PZ& p, LAS unsigned char* lds, int wave, int lane) {
;     ...
;         f32x4 St[4][4];
; #pragma unroll
;         for (int i = 0; i < 4; ++i)
; #pragma unroll
;             for (int k = 0; k < 4; ++k) St[i][k] = (f32x4){0.f, 0.f, 0.f, 0.f};
;         u32x4 stg[6]; bf16x8 awd[2], aad[2];
;         {
;             const long mcn = (long)b * TT + tok_of(dir, 0);
;             if (half == 0) {
; #pragma unroll
;                 for (int i = 0; i < 6; ++i) {
;                     const int q = lane + 64 * i, t = q / 24, rem = q - 24 * t, mat = rem >> 3, pc = rem & 7;
;                     stg[i] = *(const u32x4*)(rkv + (mcn + sgn * t) * 3072 + mat * 1024 + h * 64 + pc * 8);
;                 }
;             } else {
; #pragma unroll
;                 for (int i = 0; i < 6; ++i) stg[i] = (u32x4){0u, 0u, 0u, 0u};
;             }
;             const long mAn = mcn + sgn * (lane & 15);
; #pragma unroll
;             for (int ks = 0; ks < 2; ++ks) { awd[ks] = *(const bf16x8*)(LR + mAn * 256 + dir * 64 + ks * 32 + (lane >> 4) * 8); aad[ks] = *(const bf16x8*)(LR + mAn * 256 + 128 + dir * 64 + ks * 32 + (lane >> 4) * 8); }
;         }
.LBB0_59:
	v_lshl_add_u64 v[0:1], s[36:37], 0, v[194:195]
	v_lshlrev_b64 v[0:1], 9, v[0:1]
	v_lshl_add_u64 v[0:1], v[196:197], 0, v[0:1]
	global_load_dwordx4 v[124:127], v[0:1], off
	global_load_dwordx4 v[116:119], v[0:1], off offset:64
	global_load_dwordx4 v[120:123], v[0:1], off offset:256
	global_load_dwordx4 v[112:115], v[0:1], off offset:320
	s_lshl_b32 s12, s43, 7
	s_add_u32 s60, s69, s12
	s_addc_u32 s61, s90, 0
	s_lshl_b32 s12, s42, 13
	s_or_b32 s12, s12, s22
	s_add_u32 s12, s58, s12
	s_addc_u32 s14, s59, 0
	s_add_u32 s74, s12, 0x7050000
	s_addc_u32 s75, s14, 0
	s_lshl_b32 s30, s43, 1
	s_add_u32 s36, s15, s30
	s_addc_u32 s37, s3, 0
	s_lshl_b32 s12, s42, 2
	v_mov_b32_e32 v2, v3
	s_add_u32 s52, s6, s12
	v_mov_b32_e32 v0, v3
	v_mov_b32_e32 v1, v3
	v_mov_b64_e32 v[14:15], v[2:3]
	v_mov_b64_e32 v[18:19], v[2:3]
	v_mov_b64_e32 v[26:27], v[2:3]
	v_mov_b64_e32 v[22:23], v[2:3]
	v_mov_b64_e32 v[34:35], v[2:3]
	v_mov_b64_e32 v[42:43], v[2:3]
	v_mov_b64_e32 v[82:83], v[2:3]
	v_mov_b64_e32 v[30:31], v[2:3]
	v_mov_b64_e32 v[38:39], v[2:3]
	v_mov_b64_e32 v[46:47], v[2:3]
	v_mov_b64_e32 v[54:55], v[2:3]
	v_mov_b64_e32 v[50:51], v[2:3]
	v_mov_b64_e32 v[58:59], v[2:3]
	v_mov_b64_e32 v[66:67], v[2:3]
	v_mov_b64_e32 v[70:71], v[2:3]
	v_mov_b64_e32 v[74:75], v[2:3]
	s_addc_u32 s53, s7, 0
	s_mov_b32 s54, 0
	v_mov_b64_e32 v[12:13], v[0:1]
	v_mov_b64_e32 v[16:17], v[0:1]
	v_mov_b64_e32 v[24:25], v[0:1]
	v_mov_b64_e32 v[20:21], v[0:1]
	v_mov_b64_e32 v[32:33], v[0:1]
	v_mov_b64_e32 v[40:41], v[0:1]
	v_mov_b64_e32 v[80:81], v[0:1]
	v_mov_b64_e32 v[28:29], v[0:1]
	v_mov_b64_e32 v[36:37], v[0:1]
	v_mov_b64_e32 v[44:45], v[0:1]
	v_mov_b64_e32 v[52:53], v[0:1]
	v_mov_b64_e32 v[48:49], v[0:1]
	v_mov_b64_e32 v[56:57], v[0:1]
	v_mov_b64_e32 v[64:65], v[0:1]
	v_mov_b64_e32 v[68:69], v[0:1]
	v_mov_b64_e32 v[72:73], v[0:1]
	v_ashrrev_i32_e32 v236, 4, v166
	v_and_b32_e32 v238, 15, v166
	v_lshlrev_b32_e32 v236, 4, v236
	v_lshl_or_b32 v238, v238, 6, s13
	v_lshl_add_u32 v251, v238, 1, v236
	s_cmp_lt_i32 s62, 0
	s_cselect_b32 s12, 15, 0
	v_mov_b32_e32 v236, v166
	v_mul_u32_u24_e32 v237, 0xaab, v236
	v_lshrrev_b32_e32 v237, 16, v237
	v_mul_u32_u24_e32 v238, 24, v237
	v_sub_u32_e32 v238, v236, v238
	v_mul_u32_u24_e32 v239, 0x190, v237
	v_lshl_add_u32 v239, v238, 4, v239
	v_add_u32_e32 v239, s4, v239
	v_mul_i32_i24_e32 v236, s62, v237
	v_add_u32_e32 v236, s12, v236
	v_mul_u32_u24_e32 v236, 0x180, v236
	v_lshrrev_b32_e32 v237, 3, v238
	v_and_b32_e32 v238, 7, v238
	v_lshl_add_u32 v236, v237, 7, v236
	v_add_u32_e32 v236, v236, v238
	v_lshl_or_b32 v245, v236, 17, v239
	v_add_u32_e32 v236, 64, v166
	v_mul_u32_u24_e32 v237, 0xaab, v236
	v_lshrrev_b32_e32 v237, 16, v237
	v_mul_u32_u24_e32 v238, 24, v237
	v_sub_u32_e32 v238, v236, v238
	v_mul_u32_u24_e32 v239, 0x190, v237
	v_lshl_add_u32 v239, v238, 4, v239
	v_add_u32_e32 v239, s4, v239
	v_mul_i32_i24_e32 v236, s62, v237
	v_add_u32_e32 v236, s12, v236
	v_mul_u32_u24_e32 v236, 0x180, v236
	v_lshrrev_b32_e32 v237, 3, v238
	v_and_b32_e32 v238, 7, v238
	v_lshl_add_u32 v236, v237, 7, v236
	v_add_u32_e32 v236, v236, v238
	v_lshl_or_b32 v246, v236, 17, v239
	v_add_u32_e32 v236, 128, v166
	v_mul_u32_u24_e32 v237, 0xaab, v236
	v_lshrrev_b32_e32 v237, 16, v237
	v_mul_u32_u24_e32 v238, 24, v237
	v_sub_u32_e32 v238, v236, v238
	v_mul_u32_u24_e32 v239, 0x190, v237
	v_lshl_add_u32 v239, v238, 4, v239
	v_add_u32_e32 v239, s4, v239
	v_mul_i32_i24_e32 v236, s62, v237
	v_add_u32_e32 v236, s12, v236
	v_mul_u32_u24_e32 v236, 0x180, v236
	v_lshrrev_b32_e32 v237, 3, v238
	v_and_b32_e32 v238, 7, v238
	v_lshl_add_u32 v236, v237, 7, v236
	v_add_u32_e32 v236, v236, v238
	v_lshl_or_b32 v247, v236, 17, v239
	v_add_u32_e32 v236, 192, v166
	v_mul_u32_u24_e32 v237, 0xaab, v236
	v_lshrrev_b32_e32 v237, 16, v237
	v_mul_u32_u24_e32 v238, 24, v237
	v_sub_u32_e32 v238, v236, v238
	v_mul_u32_u24_e32 v239, 0x190, v237
	v_lshl_add_u32 v239, v238, 4, v239
	v_add_u32_e32 v239, s4, v239
	v_mul_i32_i24_e32 v236, s62, v237
	v_add_u32_e32 v236, s12, v236
	v_mul_u32_u24_e32 v236, 0x180, v236
	v_lshrrev_b32_e32 v237, 3, v238
	v_and_b32_e32 v238, 7, v238
	v_lshl_add_u32 v236, v237, 7, v236
	v_add_u32_e32 v236, v236, v238
	v_lshl_or_b32 v248, v236, 17, v239
	v_add_u32_e32 v236, 256, v166
	v_mul_u32_u24_e32 v237, 0xaab, v236
	v_lshrrev_b32_e32 v237, 16, v237
	v_mul_u32_u24_e32 v238, 24, v237
	v_sub_u32_e32 v238, v236, v238
	v_mul_u32_u24_e32 v239, 0x190, v237
	v_lshl_add_u32 v239, v238, 4, v239
	v_add_u32_e32 v239, s4, v239
	v_mul_i32_i24_e32 v236, s62, v237
	v_add_u32_e32 v236, s12, v236
	v_mul_u32_u24_e32 v236, 0x180, v236
	v_lshrrev_b32_e32 v237, 3, v238
	v_and_b32_e32 v238, 7, v238
	v_lshl_add_u32 v236, v237, 7, v236
	v_add_u32_e32 v236, v236, v238
	v_lshl_or_b32 v249, v236, 17, v239
	v_add_u32_e32 v236, 320, v166
	v_mul_u32_u24_e32 v237, 0xaab, v236
	v_lshrrev_b32_e32 v237, 16, v237
	v_mul_u32_u24_e32 v238, 24, v237
	v_sub_u32_e32 v238, v236, v238
	v_mul_u32_u24_e32 v239, 0x190, v237
	v_lshl_add_u32 v239, v238, 4, v239
	v_add_u32_e32 v239, s4, v239
	v_mul_i32_i24_e32 v236, s62, v237
	v_add_u32_e32 v236, s12, v236
	v_mul_u32_u24_e32 v236, 0x180, v236
	v_lshrrev_b32_e32 v237, 3, v238
	v_and_b32_e32 v238, 7, v238
	v_lshl_add_u32 v236, v237, 7, v236
	v_add_u32_e32 v236, v236, v238
	v_lshl_or_b32 v250, v236, 17, v239
	s_waitcnt vmcnt(0)
; #define LAS __attribute__((address_space(3)))
; DI void rwkv_chunk_scan_phase(const PZ& p, LAS unsigned char* lds, int wave, int lane) {
;     ...
;         for (int chunk = 0; chunk < TT / 16; ++chunk) {
;             const long mc0 = (long)b * TT + tok_of(dir, chunk * 16);
;             int ln = lane; asm volatile("" : "+v"(ln));
;             const int l15 = ln & 15, g = ln >> 4;
;             const bf16x8 awd0 = awd[0], awd1 = awd[1], aad0 = aad[0], aad1 = aad[1];
;             {
;                 int lq = ln;
;                 if (half == 0) {
; #pragma unroll
;                     for (int i = 0; i < 6; ++i) {
;                         const int q = lq + 64 * i, t = q / 24, rem = q - 24 * t, mat = rem >> 3, pc = rem & 7;
;                         *(LAS u32x4*)(RK + t * 200 + mat * 64 + pc * 8) = stg[i];
;                     }
;                 }
;                 if (chunk + 1 < TT / 16) {
;                     const long mcn = (long)b * TT + tok_of(dir, (chunk + 1) * 16);
;                     if (half == 0) {
; #pragma unroll
;                         for (int i = 0; i < 6; ++i) {
;                             const int q = lq + 64 * i, t = q / 24, rem = q - 24 * t, mat = rem >> 3, pc = rem & 7;
;                             stg[i] = *(const u32x4*)(rkv + (mcn + sgn * t) * 3072 + mat * 1024 + h * 64 + pc * 8);
;                         }
;                     }
;                     const long mAn = mcn + sgn * l15;
; #pragma unroll
;                     for (int ks = 0; ks < 2; ++ks) { awd[ks] = *(const bf16x8*)(LR + mAn * 256 + dir * 64 + ks * 32 + g * 8); aad[ks] = *(const bf16x8*)(LR + mAn * 256 + 128 + dir * 64 + ks * 32 + g * 8); }
;                 }
.LBB0_60:
	v_mov_b32_e32 v153, v166
	global_load_dwordx4 v[212:215], v251, s[60:61]
	global_load_dwordx4 v[216:219], v251, s[74:75]
	global_load_dwordx4 v[220:223], v251, s[60:61] offset:64
	global_load_dwordx4 v[224:227], v251, s[74:75] offset:64
	global_load_dwordx4 v[228:231], v251, s[60:61] offset:2048
	global_load_dwordx4 v[236:239], v251, s[74:75] offset:2048
	global_load_dwordx4 v[240:243], v251, s[60:61] offset:2112
	global_load_dwordx4 v[136:139], v251, s[74:75] offset:2112
	s_and_b64 vcc, exec, s[40:41]
	s_cbranch_vccnz .LBB0_62
	v_and_b32_e32 v0, 0x1ffff, v245
	ds_write_b128 v0, v[4:7] offset:19456
	v_and_b32_e32 v1, 0x1ffff, v246
	ds_write_b128 v1, v[8:11] offset:19456
	v_and_b32_e32 v0, 0x1ffff, v247
	ds_write_b128 v0, v[60:63] offset:19456
	v_and_b32_e32 v1, 0x1ffff, v248
	ds_write_b128 v1, v[76:79] offset:19456
	v_and_b32_e32 v0, 0x1ffff, v249
	ds_write_b128 v0, v[84:87] offset:19456
	v_and_b32_e32 v1, 0x1ffff, v250
	ds_write_b128 v1, v[88:91] offset:19456
.LBB0_62:
	s_add_i32 s93, s54, 1
	v_and_b32_e32 v199, 15, v153
	s_cmpk_eq_i32 s54, 0x8f
	v_ashrrev_i32_e32 v152, 4, v153
	s_cbranch_scc1 .LBB0_66
	s_lshl_b32 s12, s93, 4
	s_cmp_gt_u32 s54, 14
	s_cselect_b32 s14, s64, 0xff
	s_sub_i32 s14, s14, s12
	s_and_b64 s[42:43], s[34:35], exec
	s_cselect_b32 s12, s12, s14
	s_ashr_i32 s14, s12, 31
	s_add_u32 s42, s50, s12
	s_addc_u32 s43, s51, s14
	s_and_b64 vcc, exec, s[40:41]
	s_cbranch_vccnz .LBB0_65
	s_cmp_lt_i32 s62, 0
	s_cselect_b32 s12, 15, 0
	s_sub_i32 s12, s42, s12
	s_mul_i32 s12, s12, 0x1800
	s_add_u32 s44, s26, s12
	s_addc_u32 s45, s27, 0
	s_add_u32 s44, s44, s30
	s_addc_u32 s45, s45, 0
	v_and_b32_e32 v0, 0xfffe0000, v245
	v_lshrrev_b32_e32 v0, 13, v0
	global_load_dwordx4 v[4:7], v0, s[44:45]
	v_and_b32_e32 v1, 0xfffe0000, v246
	v_lshrrev_b32_e32 v1, 13, v1
	global_load_dwordx4 v[8:11], v1, s[44:45]
	v_and_b32_e32 v0, 0xfffe0000, v247
	v_lshrrev_b32_e32 v0, 13, v0
	global_load_dwordx4 v[60:63], v0, s[44:45]
	v_and_b32_e32 v1, 0xfffe0000, v248
	v_lshrrev_b32_e32 v1, 13, v1
	global_load_dwordx4 v[76:79], v1, s[44:45]
	v_and_b32_e32 v0, 0xfffe0000, v249
	v_lshrrev_b32_e32 v0, 13, v0
	global_load_dwordx4 v[84:87], v0, s[44:45]
	v_and_b32_e32 v1, 0xfffe0000, v250
	v_lshrrev_b32_e32 v1, 13, v1
	global_load_dwordx4 v[88:91], v1, s[44:45]

; #define MFMA16(a, b, c) __builtin_amdgcn_mfma_f32_16x16x32_bf16((a), (b), (c), 0, 0, 0)
; DI void rwkv_chunk_scan_phase(const PZ& p, LAS unsigned char* lds, int wave, int lane) {
;     ...
;             f32x4 accW[2], accA[2];
; #pragma unroll
;             for (int n2 = 0; n2 < 2; ++n2) {
;                 const int nt = 2 * half + n2;
;                 accW[n2] = (f32x4){0.f, 0.f, 0.f, 0.f}; accA[n2] = accW[n2];
; #pragma unroll
;                 for (int ks = 0; ks < 2; ++ks) {
;                     const bf16x8 wf = *(const bf16x8*)(wupT + (nt * 16 + l15) * 64 + ks * 32 + g * 8);
;                     const bf16x8 af = *(const bf16x8*)(aupT + (nt * 16 + l15) * 64 + ks * 32 + g * 8);
;                     accW[n2] = MFMA16(ks ? awd1 : awd0, wf, accW[n2]); accA[n2] = MFMA16(ks ? aad1 : aad0, af, accA[n2]);
;                 }
;             }
;             float boff[2], bb[4][2], bC[2];
; #pragma unroll
;             for (int n2 = 0; n2 < 2; ++n2) {
;                 const int nt = 2 * half + n2;
;                 const float w0v = PRM[nt * 16 + l15];
;                 float lwj[4];
; #pragma unroll
;                 for (int j = 0; j < 4; ++j) {
;                     const float xn = -(w0v + accW[n2][j]);
;                     const float sp = fmaxf(xn, 0.f) + __logf(1.f + __expf(-fabsf(xn)));
;                     lwj[j] = -__expf(-sp - 0.5f);
;                 }
;                 const float p0 = lwj[0], p1 = p0 + lwj[1], p2 = p1 + lwj[2], p3 = p2 + lwj[3];
;                 const float t1 = __shfl(p3, (ln + 48) & 63);
;                 const float s1 = p3 + (g >= 1 ? t1 : 0.f);
;                 const float t2 = __shfl(s1, (ln + 32) & 63);
;                 const float s2 = s1 + (g >= 2 ? t2 : 0.f);
;                 const float off = s2 - p3;
;                 bb[0][n2] = p0 + off; bb[1][n2] = p1 + off; bb[2][n2] = p2 + off; bb[3][n2] = p3 + off; boff[n2] = off;
.Lrw_wd:
	v_lshlrev_b32_e32 v0, 3, v152
	v_lshl_add_u32 v1, v199, 2, s71
	v_add_u32_e32 v1, 0x4400, v1
	v_add_u32_e32 v2, 48, v153
	v_and_or_b32 v2, v2, 63, v200
	v_cmp_lt_i32_e32 vcc, 0, v152
	v_cmp_lt_i32_e64 s[42:43], 1, v152
	s_movk_i32 s12, 0x640
	v_mfma_f32_16x16x32_bf16 v[108:111], v[124:127], v[212:215], 0
	v_mfma_f32_16x16x32_bf16 v[132:135], v[120:123], v[216:219], 0
	v_mfma_f32_16x16x32_bf16 v[128:131], v[116:119], v[220:223], v[108:111]
	v_mfma_f32_16x16x32_bf16 v[108:111], v[112:115], v[224:227], v[132:135]
	v_mfma_f32_16x16x32_bf16 v[124:127], v[124:127], v[228:231], 0
	v_mfma_f32_16x16x32_bf16 v[120:123], v[120:123], v[236:239], 0
	v_mfma_f32_16x16x32_bf16 v[116:119], v[116:119], v[240:243], v[124:127]
	v_mfma_f32_16x16x32_bf16 v[112:115], v[112:115], v[136:139], v[120:123]
	s_nop 5
	ds_read2_b32 v[120:121], v1 offset0:192 offset1:208
	v_lshlrev_b32_e32 v122, 2, v2
	v_and_or_b32 v2, v153, 63, v200
	v_lshlrev_b32_e32 v2, 2, v2
	v_xor_b32_e32 v123, 0x80, v2
	s_waitcnt lgkmcnt(0)
	v_add_f32_e32 v1, v128, v120
	v_max_f32_e64 v124, -v1, 0
	v_mul_f32_e64 v1, |v1|, s57
	v_exp_f32_e32 v1, v1
	v_add_f32_e32 v116, v116, v121
	v_or_b32_e32 v2, v199, v200
	v_lshlrev_b32_e32 v2, 2, v2
	v_add_f32_e32 v1, 1.0, v1
	v_cmp_gt_f32_e64 s[44:45], s1, v1
	s_nop 1
	v_cndmask_b32_e64 v125, 0, 32, s[44:45]
	v_ldexp_f32 v1, v1, v125
	v_log_f32_e32 v1, v1
	s_nop 0
	v_mul_f32_e32 v125, 0x3f317217, v1
	v_fma_f32 v125, v1, s94, -v125
	v_fmac_f32_e32 v125, 0x3377d1cf, v1
	v_fmac_f32_e32 v125, 0x3f317217, v1
	v_cmp_lt_f32_e64 s[46:47], |v1|, s95
	s_nop 1
	v_cndmask_b32_e64 v1, v1, v125, s[46:47]
	v_cndmask_b32_e64 v125, 0, v206, s[44:45]
	v_sub_f32_e32 v1, v1, v125
	v_add_f32_e32 v1, v124, v1
	v_add_f32_e32 v124, v129, v120
	v_max_f32_e64 v125, -v124, 0
	v_mul_f32_e64 v124, |v124|, s57
	v_exp_f32_e32 v124, v124
	v_sub_f32_e32 v1, -0.5, v1
	v_mul_f32_e32 v1, 0x3fb8aa3b, v1
	v_exp_f32_e32 v1, v1
	v_add_f32_e32 v124, 1.0, v124
	v_cmp_gt_f32_e64 s[44:45], s1, v124
	s_nop 1
	v_cndmask_b32_e64 v126, 0, 32, s[44:45]
	v_ldexp_f32 v124, v124, v126
	v_log_f32_e32 v124, v124
	s_nop 0
	v_mul_f32_e32 v126, 0x3f317217, v124
	v_fma_f32 v126, v124, s94, -v126
	v_fmac_f32_e32 v126, 0x3377d1cf, v124
	v_fmac_f32_e32 v126, 0x3f317217, v124
	v_cmp_lt_f32_e64 s[46:47], |v124|, s95
	s_nop 1
	v_cndmask_b32_e64 v124, v124, v126, s[46:47]
	v_cndmask_b32_e64 v126, 0, v206, s[44:45]
	v_sub_f32_e32 v124, v124, v126
	v_add_f32_e32 v124, v125, v124
	v_add_f32_e32 v125, v130, v120
	v_max_f32_e64 v126, -v125, 0
	v_mul_f32_e64 v125, |v125|, s57
	v_exp_f32_e32 v125, v125
	v_add_f32_e32 v120, v131, v120
	v_sub_f32_e32 v124, -0.5, v124
	v_mul_f32_e32 v124, 0x3fb8aa3b, v124
	v_add_f32_e32 v125, 1.0, v125
	v_cmp_gt_f32_e64 s[44:45], s1, v125
	v_exp_f32_e32 v124, v124
	s_nop 0
	v_cndmask_b32_e64 v127, 0, 32, s[44:45]
	v_ldexp_f32 v125, v125, v127
	v_log_f32_e32 v125, v125
	v_sub_f32_e64 v217, -v124, v1
	v_mul_f32_e32 v127, 0x3f317217, v125
	v_fma_f32 v127, v125, s94, -v127
	v_fmac_f32_e32 v127, 0x3377d1cf, v125
	v_fmac_f32_e32 v127, 0x3f317217, v125
	v_cmp_lt_f32_e64 s[46:47], |v125|, s95
	s_nop 1
	v_cndmask_b32_e64 v125, v125, v127, s[46:47]
	v_cndmask_b32_e64 v127, 0, v206, s[44:45]
	v_sub_f32_e32 v125, v125, v127
	v_add_f32_e32 v125, v126, v125
	v_max_f32_e64 v126, -v120, 0
	v_mul_f32_e64 v120, |v120|, s57
	v_exp_f32_e32 v120, v120
	v_sub_f32_e32 v125, -0.5, v125
	v_mul_f32_e32 v125, 0x3fb8aa3b, v125
	v_exp_f32_e32 v125, v125
	v_add_f32_e32 v120, 1.0, v120
	v_cmp_gt_f32_e64 s[44:45], s1, v120
	v_sub_f32_e32 v216, v217, v125
	s_nop 0
	v_cndmask_b32_e64 v127, 0, 32, s[44:45]
	v_ldexp_f32 v120, v120, v127
	v_log_f32_e32 v120, v120
	s_nop 0
	v_mul_f32_e32 v127, 0x3f317217, v120
	v_fma_f32 v127, v120, s94, -v127
	v_fmac_f32_e32 v127, 0x3377d1cf, v120
	v_fmac_f32_e32 v127, 0x3f317217, v120
	v_cmp_lt_f32_e64 s[46:47], |v120|, s95
	s_nop 1
	v_cndmask_b32_e64 v120, v120, v127, s[46:47]
	v_cndmask_b32_e64 v127, 0, v206, s[44:45]
	v_sub_f32_e32 v120, v120, v127
	v_add_f32_e32 v120, v126, v120
	v_sub_f32_e32 v120, -0.5, v120
	v_mul_f32_e32 v120, 0x3fb8aa3b, v120
	v_exp_f32_e32 v120, v120
	s_nop 0
	v_sub_f32_e32 v151, v216, v120
	ds_bpermute_b32 v120, v122, v151
	s_waitcnt lgkmcnt(0)
	v_cndmask_b32_e32 v120, 0, v120, vcc
	v_add_f32_e32 v120, v120, v151
	ds_bpermute_b32 v124, v123, v120
	s_waitcnt lgkmcnt(0)
; DI float bf2f(unsigned short u) { return __uint_as_float((unsigned)u << 16); }
; DI float red16(float v) { v += DPPF(v, 0xB1); v += DPPF(v, 0x4E); v += DPPF(v, 0x141); v += DPPF(v, 0x140); return v; }
; DI void rwkv_chunk_scan_phase(const PZ& p, LAS unsigned char* lds, int wave, int lane) {
;     ...
;             float boff[2], bb[4][2], bC[2];
; #pragma unroll
;             for (int n2 = 0; n2 < 2; ++n2) {
;                 const int nt = 2 * half + n2;
;                 const float w0v = PRM[nt * 16 + l15];
;                 float lwj[4];
; #pragma unroll
;                 for (int j = 0; j < 4; ++j) {
;                     const float xn = -(w0v + accW[n2][j]);
;                     const float sp = fmaxf(xn, 0.f) + __logf(1.f + __expf(-fabsf(xn)));
;                     lwj[j] = -__expf(-sp - 0.5f);
;                 }
;                 const float p0 = lwj[0], p1 = p0 + lwj[1], p2 = p1 + lwj[2], p3 = p2 + lwj[3];
;                 const float t1 = __shfl(p3, (ln + 48) & 63);
;                 const float s1 = p3 + (g >= 1 ? t1 : 0.f);
;                 const float t2 = __shfl(s1, (ln + 32) & 63);
;                 const float s2 = s1 + (g >= 2 ? t2 : 0.f);
;                 const float off = s2 - p3;
;                 bb[0][n2] = p0 + off; bb[1][n2] = p1 + off; bb[2][n2] = p2 + off; bb[3][n2] = p3 + off; boff[n2] = off;
;                 bC[n2] = __shfl(s2, 48 + l15);
;             }
;             float av[4][2], kr[4][2], kdv[4][2], rv[4][2];
; #pragma unroll
;             for (int j = 0; j < 4; ++j) {
;                 const int t = g * 4 + j;
;                 float ss = 0.f, bsum = 0.f;
; #pragma unroll
;                 for (int n2 = 0; n2 < 2; ++n2) {
;                     const int c = (2 * half + n2) * 16 + l15;
;                     const float r_ = bf2f(RK[t * 200 + c]), k_ = bf2f(RK[t * 200 + 64 + c]);
;                     const float a_ = __builtin_amdgcn_rcpf(1.f + __expf(-(PRM[64 + c] + accA[n2][j])));
;                     kr[j][n2] = k_ * PRM[128 + c]; ss += kr[j][n2] * kr[j][n2]; av[j][n2] = a_; rv[j][n2] = r_;
;                     kdv[j][n2] = k_ * (1.f + (a_ - 1.f) * PRM[192 + c]);
;                     bsum += r_ * kdv[j][n2] * PRM[256 + c];
;                 }
;                 ss = red16(ss); bsum = red16(bsum);
;                 if (l15 == 0) { EX[(half * 16 + t) * 2] = ss; EX[(half * 16 + t) * 2 + 1] = bsum; }
	v_cndmask_b32_e64 v124, 0, v124, s[42:43]
	v_add_f32_e32 v218, v124, v120
	v_max_f32_e64 v120, -v116, 0
	v_mul_f32_e64 v116, |v116|, s57
	v_exp_f32_e32 v116, v116
	ds_bpermute_b32 v214, v2, v218 offset:192
	v_add_f32_e32 v116, 1.0, v116
	v_cmp_gt_f32_e64 s[44:45], s1, v116
	s_nop 1
	v_cndmask_b32_e64 v124, 0, 32, s[44:45]
	v_ldexp_f32 v116, v116, v124
	v_log_f32_e32 v116, v116
	s_nop 0
	v_mul_f32_e32 v124, 0x3f317217, v116
	v_fma_f32 v124, v116, s94, -v124
	v_fmac_f32_e32 v124, 0x3377d1cf, v116
	v_fmac_f32_e32 v124, 0x3f317217, v116
	v_cmp_lt_f32_e64 s[46:47], |v116|, s95
	s_nop 1
	v_cndmask_b32_e64 v116, v116, v124, s[46:47]
	v_cndmask_b32_e64 v124, 0, v206, s[44:45]
	v_sub_f32_e32 v116, v116, v124
	v_add_f32_e32 v116, v120, v116
	v_sub_f32_e32 v116, -0.5, v116
	v_mul_f32_e32 v116, 0x3fb8aa3b, v116
	v_exp_f32_e32 v220, v116
	v_add_f32_e32 v116, v117, v121
	v_max_f32_e64 v117, -v116, 0
	v_mul_f32_e64 v116, |v116|, s57
	v_exp_f32_e32 v116, v116
	s_nop 0
	v_add_f32_e32 v116, 1.0, v116
	v_cmp_gt_f32_e64 s[44:45], s1, v116
	s_nop 1
	v_cndmask_b32_e64 v120, 0, 32, s[44:45]
	v_ldexp_f32 v116, v116, v120
	v_log_f32_e32 v116, v116
	s_nop 0
	v_mul_f32_e32 v120, 0x3f317217, v116
	v_fma_f32 v120, v116, s94, -v120
	v_fmac_f32_e32 v120, 0x3377d1cf, v116
	v_fmac_f32_e32 v120, 0x3f317217, v116
	v_cmp_lt_f32_e64 s[46:47], |v116|, s95
	s_nop 1
	v_cndmask_b32_e64 v116, v116, v120, s[46:47]
	v_cndmask_b32_e64 v120, 0, v206, s[44:45]
	v_sub_f32_e32 v116, v116, v120
	v_add_f32_e32 v116, v117, v116
	v_add_f32_e32 v117, v118, v121
	v_max_f32_e64 v118, -v117, 0
	v_mul_f32_e64 v117, |v117|, s57
	v_exp_f32_e32 v117, v117
	v_sub_f32_e32 v116, -0.5, v116
	v_mul_f32_e32 v116, 0x3fb8aa3b, v116
	v_exp_f32_e32 v116, v116
	v_add_f32_e32 v117, 1.0, v117
	v_cmp_gt_f32_e64 s[44:45], s1, v117
	v_sub_f32_e64 v221, -v116, v220
	s_nop 0
	v_cndmask_b32_e64 v120, 0, 32, s[44:45]
	v_ldexp_f32 v117, v117, v120
	v_log_f32_e32 v117, v117
	s_nop 0
	v_mul_f32_e32 v120, 0x3f317217, v117
	v_fma_f32 v120, v117, s94, -v120
	v_fmac_f32_e32 v120, 0x3377d1cf, v117
	v_fmac_f32_e32 v120, 0x3f317217, v117
	v_cmp_lt_f32_e64 s[46:47], |v117|, s95
	s_nop 1
	v_cndmask_b32_e64 v117, v117, v120, s[46:47]
	v_cndmask_b32_e64 v120, 0, v206, s[44:45]
	v_sub_f32_e32 v117, v117, v120
	v_add_f32_e32 v117, v118, v117
	v_add_f32_e32 v118, v119, v121
	v_max_f32_e64 v119, -v118, 0
	v_mul_f32_e64 v118, |v118|, s57
	v_exp_f32_e32 v118, v118
	v_sub_f32_e32 v117, -0.5, v117
	v_mul_f32_e32 v117, 0x3fb8aa3b, v117
	v_exp_f32_e32 v117, v117
	v_add_f32_e32 v118, 1.0, v118
	v_cmp_gt_f32_e64 s[44:45], s1, v118
	v_sub_f32_e32 v219, v221, v117
	s_nop 0
	v_cndmask_b32_e64 v120, 0, 32, s[44:45]
	v_ldexp_f32 v118, v118, v120
	v_log_f32_e32 v118, v118
	s_nop 0
	v_mul_f32_e32 v120, 0x3f317217, v118
	v_fma_f32 v120, v118, s94, -v120
	v_fmac_f32_e32 v120, 0x3377d1cf, v118
	v_fmac_f32_e32 v120, 0x3f317217, v118
	v_cmp_lt_f32_e64 s[46:47], |v118|, s95
	s_nop 1
	v_cndmask_b32_e64 v118, v118, v120, s[46:47]
	v_cndmask_b32_e64 v120, 0, v206, s[44:45]
	v_sub_f32_e32 v118, v118, v120
	v_add_f32_e32 v118, v119, v118
	v_sub_f32_e32 v118, -0.5, v118
	v_mul_f32_e32 v118, 0x3fb8aa3b, v118
	v_exp_f32_e32 v118, v118
	s_nop 0
	v_sub_f32_e32 v117, v219, v118
	ds_bpermute_b32 v116, v122, v117
	s_waitcnt lgkmcnt(0)
	v_cndmask_b32_e32 v116, 0, v116, vcc
	v_add_f32_e32 v116, v116, v117
	ds_bpermute_b32 v118, v123, v116
	s_waitcnt lgkmcnt(0)
	v_cndmask_b32_e64 v118, 0, v118, s[42:43]
	v_add_f32_e32 v225, v118, v116
	ds_bpermute_b32 v223, v2, v225 offset:192
	v_mul_lo_u32 v2, v152, s12
	v_or_b32_e32 v116, s92, v199
	v_add_u32_e32 v150, s4, v2
	v_lshl_add_u32 v2, v116, 1, v150
	ds_read_u16 v118, v2 offset:19456
	ds_read_u16 v120, v2 offset:19488
	v_cmp_eq_u32_e64 s[42:43], 0, v199
	s_waitcnt lgkmcnt(1)
	v_lshlrev_b32_e32 v222, 16, v118
	v_lshl_add_u32 v118, v116, 2, s4
	v_add_u32_e32 v229, 0x4800, v118
	ds_read2_b32 v[124:125], v229 offset1:16
	ds_read2_b32 v[118:119], v229 offset0:64 offset1:80
	ds_read2_b32 v[136:137], v229 offset0:128 offset1:144
	ds_read2_b32 v[126:127], v229 offset0:192 offset1:208
	ds_read_u16 v121, v2 offset:19616
	ds_read_u16 v2, v2 offset:19584
	s_waitcnt lgkmcnt(5)
	v_add_f32_e32 v108, v108, v124
	v_mul_f32_e32 v108, 0xbfb8aa3b, v108
	v_exp_f32_e32 v108, v108
	v_add_f32_e32 v112, v112, v125
	v_mul_f32_e32 v112, 0xbfb8aa3b, v112
	v_exp_f32_e32 v112, v112
	v_add_f32_e32 v108, 1.0, v108
	v_rcp_f32_e32 v227, v108
	s_waitcnt lgkmcnt(1)
	v_lshlrev_b32_e32 v128, 16, v121
	v_add_f32_e32 v112, 1.0, v112
	v_rcp_f32_e32 v226, v112
	v_add_f32_e32 v108, -1.0, v227
	v_fma_f32 v108, v136, v108, 1.0
	v_lshlrev_b32_e32 v121, 16, v120
	s_waitcnt lgkmcnt(0)
	v_lshlrev_b32_e32 v120, 16, v2
	v_add_f32_e32 v112, -1.0, v226
	v_mul_f32_e32 v228, v108, v120
	v_fma_f32 v112, v137, v112, 1.0
	v_mul_f32_e32 v129, v228, v222
	v_mov_b32_e32 v140, v119
	v_mov_b32_e32 v141, v126
	v_mul_f32_e32 v224, v112, v128
	v_pk_mul_f32 v[122:123], v[140:141], v[128:129]
	v_mov_b32_e32 v119, v224
	v_mov_b32_e32 v2, v122
	v_pk_mul_f32 v[130:131], v[122:123], v[122:123]
	v_pk_fma_f32 v[128:129], v[140:141], v[128:129], v[2:3]
	v_pk_mul_f32 v[132:133], v[118:119], v[120:121]
	v_mov_b32_e32 v131, v129
	v_mov_b32_e32 v126, v132
	v_pk_fma_f32 v[128:129], v[126:127], v[132:133], v[130:131]
	s_nop 1
	v_mov_b32_dpp v130, v128 quad_perm:[1,0,3,2] row_mask:0xf bank_mask:0xf bound_ctrl:1
	v_mov_b32_dpp v131, v129 quad_perm:[1,0,3,2] row_mask:0xf bank_mask:0xf bound_ctrl:1
	v_pk_add_f32 v[128:129], v[128:129], v[130:131]
	s_nop 1
	v_mov_b32_dpp v130, v128 quad_perm:[2,3,0,1] row_mask:0xf bank_mask:0xf bound_ctrl:1
	v_mov_b32_dpp v131, v129 quad_perm:[2,3,0,1] row_mask:0xf bank_mask:0xf bound_ctrl:1
	v_pk_add_f32 v[128:129], v[128:129], v[130:131]
	s_nop 1
	v_mov_b32_dpp v130, v128 row_half_mirror row_mask:0xf bank_mask:0xf bound_ctrl:1
	v_mov_b32_dpp v131, v129 row_half_mirror row_mask:0xf bank_mask:0xf bound_ctrl:1
	v_pk_add_f32 v[128:129], v[128:129], v[130:131]
	s_nop 1
	v_mov_b32_dpp v130, v128 row_mirror row_mask:0xf bank_mask:0xf bound_ctrl:1
	v_mov_b32_dpp v131, v129 row_mirror row_mask:0xf bank_mask:0xf bound_ctrl:1
	s_and_saveexec_b64 s[44:45], s[42:43]
	s_cbranch_execz .LBB0_71
	v_lshl_add_u32 v2, v152, 5, s71
	v_pk_add_f32 v[118:119], v[128:129], v[130:131]
	ds_write_b64 v2, v[118:119] offset:25856
	ds_read2_b32 v[124:125], v229 offset1:16
	ds_read2_b32 v[118:119], v229 offset0:64 offset1:80
	ds_read2_b32 v[126:127], v229 offset0:192 offset1:208
	ds_read2_b32 v[136:137], v229 offset0:128 offset1:144
	s_waitcnt lgkmcnt(2)
	v_mov_b32_e32 v140, v119
	s_waitcnt lgkmcnt(1)
	v_mov_b32_e32 v141, v126
